# grid barrier: first arriving workgroup of each XCD starts an early L2 writeback so the last arriver's release flush has less left
# speedup vs baseline: 1.0023x; 1.0023x over previous
; DI unsigned xb_ld(unsigned* p)              { return __hip_atomic_load(p, __ATOMIC_RELAXED, __HIP_MEMORY_SCOPE_AGENT); }
; DI unsigned xb_add(unsigned* p, unsigned v) { return __hip_atomic_fetch_add(p, v, __ATOMIC_RELAXED, __HIP_MEMORY_SCOPE_AGENT); }
; #define XB_SPIN(cond, bar) do { unsigned _sp = 0; while (cond) { __builtin_amdgcn_s_sleep(1); \
;     if ((++_sp & 255u) == 0u) { if (xb_ld(&(bar)[XB_TMO])) break; if (_sp > XB_SPIN_CAP) { atomicAdd(&(bar)[XB_TMO], 1u); break; } } } } while (0)
; DI void xcd_barrier(const XcdBarrier& b) {
;     ...
;         const unsigned old = xb_add(&bar[XB_XSUB(b.x)], 1u);
;         const unsigned gen = old / nloc;
;         if (old + 1u == (gen + 1u) * nloc) {
;             __builtin_amdgcn_fence(__ATOMIC_RELEASE, "agent");
;             asm volatile("s_waitcnt vmcnt(0)" ::: "memory");
;             const unsigned og = xb_add(&bar[XB_TOP], 1u);
;             const unsigned tg = og / nx;
;             if (og + 1u == (tg + 1u) * nx) xb_add(&bar[XB_TOPGEN], 1u);
;             else XB_SPIN(xb_ld(&bar[XB_TOPGEN]) == tg, bar);
;             __builtin_amdgcn_fence(__ATOMIC_ACQUIRE, "agent");
;             xb_add(&bar[XB_XGEN(b.x)], 1u);
;             asm volatile("s_waitcnt vmcnt(0)" ::: "memory");
;         } else {
;             XB_SPIN(xb_ld(&bar[XB_XGEN(b.x)]) == gen, bar);
.LBB0_1151:
	s_or_b64 exec, exec, s[16:17]
	v_cvt_f32_u32_e32 v4, v2
	s_waitcnt vmcnt(0)
	v_readfirstlane_b32 s0, v3
	v_sub_u32_e32 v3, 0, v2
	v_rcp_iflag_f32_e32 v4, v4
	v_add_u32_e32 v5, s0, v1
	v_mul_f32_e32 v4, 0x4f7ffffe, v4
	v_cvt_u32_f32_e32 v4, v4
	v_mul_lo_u32 v1, v3, v4
	v_mul_hi_u32 v1, v4, v1
	v_add_u32_e32 v1, v4, v1
	v_mul_hi_u32 v1, v5, v1
	v_mul_lo_u32 v3, v1, v2
	v_sub_u32_e32 v3, v5, v3
	v_add_u32_e32 v4, 1, v1
	v_cmp_ge_u32_e32 vcc, v3, v2
	s_nop 1
	v_cndmask_b32_e32 v1, v1, v4, vcc
	v_sub_u32_e32 v4, v3, v2
	v_cndmask_b32_e32 v3, v3, v4, vcc
	v_add_u32_e32 v4, 1, v1
	v_cmp_ge_u32_e32 vcc, v3, v2
	v_add_u32_e32 v3, 1, v5
	s_nop 0
	v_cndmask_b32_e32 v1, v1, v4, vcc
	v_mul_lo_u32 v4, v2, v1
	v_add_u32_e32 v2, v4, v2
	v_cmp_ne_u32_e32 vcc, v3, v2
	s_and_saveexec_b64 s[16:17], vcc
	s_xor_b64 s[16:17], exec, s[16:17]
	s_cbranch_execz .LBB0_1165
	v_add_u32_e32 v227, 1, v4
	v_cmp_eq_u32_e32 vcc, v3, v227
	s_cbranch_vccz .Lbar_noearly
	buffer_wbl2 sc1
.Lbar_noearly:
	v_readlane_b32 s18, v253, 40
	v_readlane_b32 s19, v253, 41
	s_waitcnt lgkmcnt(0)
	s_nop 3
	global_load_dword v0, v12, s[18:19] sc1
	s_waitcnt vmcnt(0)
	v_cmp_eq_u32_e32 vcc, v0, v1
	s_and_saveexec_b64 s[18:19], vcc
	s_cbranch_execz .LBB0_1164
	s_mov_b32 s0, 1
	s_mov_b64 s[26:27], 0
	s_branch .LBB0_1155
